# GDN scan second half rescheduled (single pass over v_new fragments, DPP row sums); output gating fused into the scan (separate gating phase and its grid barrier dropped)
# speedup vs baseline: 1.0229x; 1.0042x over previous
; #define LAS __attribute__((address_space(3)))
; __device__ __forceinline__ void lds_barrier() { asm volatile("s_waitcnt lgkmcnt(0)" ::: "memory"); __builtin_amdgcn_s_barrier(); asm volatile("" ::: "memory"); }
; __device__ __forceinline__ void gdn_chain(LAS unsigned char* lds, const GdnP& P, const float* out_norm, int bh, const int tid) {
;     const int w = __builtin_amdgcn_readfirstlane(tid >> 6), lane = tid & 63, l15 = lane & 15, quad = lane >> 4;
;     const int b = bh >> 3, h = bh & 7, mt = w & 3, nh = w >> 2;
;     f32x4 sacc[8];
; #pragma unroll
;     for (int n = 0; n < 8; ++n) sacc[n] = (f32x4){0.f, 0.f, 0.f, 0.f};
;     lds_barrier();
;     for (int i = tid; i < 34816 / 16; i += 512) *(LAS u32x4*)(lds + GC_ST + i * 16) = (u32x4){0u, 0u, 0u, 0u};
;     ChainOps cur, nxt;
;     chain_load(cur, P, b, h, 0, w, mt, nh, lane, tid);
;     lds_barrier();
; __global__ void __launch_bounds__(NTHREADS, 2) mega(Args a) {
;     ...
;         const float* rstdo = (const float*)(ws + WS_RSTDO); const float* onorm = AIN(I_ONORM);
;         for (int idx = bx * NTHREADS + tid; idx < TOK * 64; idx += G * NTHREADS) {
;             const int token = idx >> 6, h = (idx >> 3) & 7, c16 = idx & 7;
;             const bf16_t* op = proj + (size_t)token * NIN + C_GDN + 2048 + h * 128 + c16 * 16; bf16_t* zp = proj + (size_t)token * NIN + C_Z + h * 128 + c16 * 16;
;             const u32x4 o0 = *(const u32x4*)op, o1 = *(const u32x4*)(op + 8), z0 = *(const u32x4*)zp, z1 = *(const u32x4*)(zp + 8);
;             const float rstd = rstdo[(size_t)token * 8 + h];
.LBB0_1124:
	s_or_b64 exec, exec, s[28:29]
	v_readlane_b32 s54, v253, 0
	v_readlane_b32 s55, v253, 1
	s_load_dwordx2 s[56:57], s[54:55], 0x58
	v_lshlrev_b32_e32 v220, 2, v112
	s_movk_i32 s76, 0x80
	v_cmp_gt_u32_e64 s[74:75], s76, v112
	s_and_saveexec_b64 s[70:71], s[74:75]
	s_waitcnt lgkmcnt(0)
	s_cbranch_execz .Lgf_onorm_skip
	global_load_dword v221, v220, s[56:57]
	s_waitcnt vmcnt(0)
	ds_write_b32 v220, v221 offset:53760
.Lgf_onorm_skip:
	s_or_b64 exec, exec, s[70:71]
	s_ashr_i32 s29, s42, 3
	s_ashr_i32 s46, s0, 6
	s_and_b32 s43, s42, 7
	s_ashr_i32 s48, s0, 8
	s_mov_b32 s59, s48
	s_lshl_b32 s0, s29, 9
	s_or_b32 s28, s0, s43
	s_lshl_b32 s44, s29, 6
	s_lshl_b32 s49, s29, 12
	s_ashr_i32 s29, s28, 31
	s_and_b32 s47, s46, 3
	s_lshl_b64 s[30:31], s[28:29], 14
	s_add_u32 s30, s18, s30
	s_addc_u32 s31, s19, s31
	s_lshl_b32 s50, s47, 4
	v_or_b32_e32 v152, s50, v113
	v_lshlrev_b32_e32 v26, 8, v152
	v_mov_b32_e32 v27, v115
	v_lshl_add_u64 v[0:1], s[30:31], 0, v[26:27]
	v_lshl_add_u64 v[8:9], v[0:1], 0, v[114:115]
	v_or_b32_e32 v0, s49, v152
	v_mad_i64_i32 v[0:1], s[30:31], v0, s40, v[120:121]
	s_lshl_b32 s45, s43, 7
	s_lshl_b32 s0, s43, 8
	s_lshl_b64 s[30:31], s[28:29], 13
	v_lshl_or_b32 v34, s46, 4, v113
	s_add_u32 s30, s20, s30
	v_ashrrev_i32_e32 v153, 1, v34
	v_lshlrev_b32_e32 v24, 7, v152
	v_mov_b32_e32 v25, v115
	s_addc_u32 s31, s21, s31
	v_add_u32_e32 v34, s49, v153
	v_lshl_add_u64 v[0:1], v[0:1], 0, s[0:1]
	v_lshl_add_u64 v[32:33], s[30:31], 0, v[24:25]
	v_mad_i64_i32 v[34:35], s[30:31], v34, s40, v[120:121]
	v_lshl_add_u64 v[0:1], v[0:1], 0, v[114:115]
	v_lshl_add_u64 v[34:35], v[34:35], 0, s[0:1]
	v_add_co_u32_e32 v28, vcc, s41, v0
	v_lshl_add_u64 v[34:35], v[34:35], 0, v[124:125]
	s_lshl_b64 s[28:29], s[28:29], 2
	v_addc_co_u32_e32 v29, vcc, 0, v1, vcc
	v_lshl_add_u64 v[34:35], v[34:35], 0, v[114:115]
	s_add_u32 s28, s2, s28
	v_lshl_add_u64 v[10:11], v[0:1], 0, s[22:23]
	v_lshl_add_u64 v[32:33], v[32:33], 0, v[114:115]
	v_lshl_add_u64 v[36:37], v[34:35], 0, s[24:25]
	v_add_co_u32_e32 v34, vcc, s38, v34
	s_addc_u32 s29, s3, s29
	global_load_dwordx4 v[72:75], v[8:9], off
	global_load_dwordx4 v[12:15], v[8:9], off offset:64
	global_load_dwordx4 v[4:7], v[10:11], off offset:64
	global_load_dwordx4 v[0:3], v[10:11], off offset:128
	global_load_dwordx4 v[20:23], v[8:9], off offset:128
	global_load_dwordx4 v[16:19], v[8:9], off offset:192
	s_nop 0
	global_load_dwordx4 v[28:31], v[28:29], off offset:2048
	s_nop 0
	global_load_dwordx4 v[8:11], v[10:11], off offset:192
	v_addc_co_u32_e32 v35, vcc, 0, v35, vcc
	global_load_dwordx4 v[68:71], v[32:33], off
	global_load_dwordx4 v[44:47], v[32:33], off offset:64
	global_load_dwordx4 v[48:51], v[34:35], off
	s_nop 0
	global_load_dwordx4 v[36:39], v[36:37], off offset:64
	s_lshl_b32 s30, s48, 6
	global_load_dword v123, v115, s[28:29]
	s_lshl_b32 s28, s47, 7
	s_add_i32 s28, s28, s30
	v_or_b32_e32 v32, s28, v139
	v_ashrrev_i32_e32 v154, 3, v32
	v_add_u32_e32 v32, s49, v154
	v_mad_i64_i32 v[32:33], s[28:29], v32, s40, v[120:121]
	v_lshl_add_u64 v[32:33], v[32:33], 0, s[0:1]
	v_lshl_add_u64 v[32:33], v[32:33], 0, v[128:129]
	v_lshl_add_u64 v[34:35], v[32:33], 0, s[26:27]
	v_add_co_u32_e32 v32, vcc, s38, v32
	s_lshl_b32 s0, s48, 2
	s_nop 0
	v_addc_co_u32_e32 v33, vcc, 0, v33, vcc
	global_load_dwordx4 v[80:83], v[32:33], off offset:2048
	global_load_dwordx4 v[84:87], v[34:35], off offset:16
	v_or_b32_e32 v34, s30, v113
	s_or_b32 s28, s0, 1
	v_mul_lo_u32 v35, v34, s36
	v_mul_lo_u32 v156, v34, s37
	v_lshl_or_b32 v34, s28, 4, v113
	s_or_b32 s29, s0, 2
	v_or_b32_e32 v32, s50, v142
	v_lshl_add_u32 v33, s46, 5, v141
	s_add_i32 s46, s0, 0
	v_mul_lo_u32 v40, v34, s36
	v_mul_lo_u32 v157, v34, s37
	v_lshl_or_b32 v34, s29, 4, v113
	s_or_b32 s0, s0, 3
	s_waitcnt lgkmcnt(0)
	s_barrier
	v_mul_lo_u32 v41, v34, s36
	v_mul_lo_u32 v158, v34, s37
	v_lshl_or_b32 v34, s0, 4, v113
	v_lshl_add_u32 v54, s0, 5, v143
	v_lshlrev_b32_e32 v160, 3, v32
	s_lshl_b32 s0, s43, 2
	v_mul_lo_u32 v42, v34, s36
	v_mul_lo_u32 v159, v34, s37
	v_lshl_add_u32 v34, s48, 7, v143
	v_mul_u32_u24_e32 v43, 0x110, v32
	v_lshl_add_u32 v52, s28, 5, v143
	v_lshl_add_u32 v53, s29, 5, v143
	v_or_b32_e32 v32, 8, v160
	v_or_b32_e32 v55, 16, v160
	v_or_b32_e32 v56, 24, v160
	v_lshl_add_u64 v[134:135], v[118:119], 0, v[24:25]
	s_add_u32 s28, s33, s0
	v_mov_b32_e32 v24, 0
	v_lshl_add_u32 v155, s47, 5, v141
	v_lshl_add_u64 v[132:133], v[116:117], 0, v[26:27]
	s_addc_u32 s29, s35, 0
	v_add_u32_e32 v136, s49, v144
	s_movk_i32 s47, 0xffc0
	v_add_u32_e32 v161, v140, v35
	v_add_u32_e32 v162, v140, v40
	v_add_u32_e32 v163, v140, v41
	v_add_u32_e32 v164, v140, v42
	v_add_u32_e32 v165, v34, v43
	v_add_u32_e32 v166, v52, v43
	v_add_u32_e32 v167, v53, v43
	v_add_u32_e32 v168, v54, v43
	v_add_u32_e32 v169, v33, v145
	v_add_u32_e32 v170, s46, v32
	v_add_u32_e32 v171, s46, v55
	v_add_u32_e32 v172, s46, v56
	v_mov_b32_e32 v25, v24
	v_mov_b32_e32 v26, v24
	v_mov_b32_e32 v27, v24
	v_mov_b32_e32 v32, v24
	v_mov_b32_e32 v33, v24
	v_mov_b32_e32 v34, v24
	v_mov_b32_e32 v35, v24
	v_mov_b32_e32 v40, v24
	v_mov_b32_e32 v41, v24
	v_mov_b32_e32 v42, v24
	v_mov_b32_e32 v43, v24
	v_mov_b32_e32 v52, v24
	v_mov_b32_e32 v53, v24
	v_mov_b32_e32 v54, v24
	v_mov_b32_e32 v55, v24
	v_mov_b32_e32 v56, v24
	v_mov_b32_e32 v57, v24
	v_mov_b32_e32 v58, v24
	v_mov_b32_e32 v59, v24
	v_mov_b32_e32 v60, v24
	v_mov_b32_e32 v61, v24
	v_mov_b32_e32 v62, v24
	v_mov_b32_e32 v63, v24
	v_mov_b32_e32 v64, v24
	v_mov_b32_e32 v65, v24
	v_mov_b32_e32 v66, v24
	v_mov_b32_e32 v67, v24
	v_mov_b32_e32 v76, v24
	v_mov_b32_e32 v77, v24
	v_mov_b32_e32 v78, v24
	v_mov_b32_e32 v79, v24
	v_mov_b32_e32 v222, v130
	v_mov_b32_e32 v223, 0
	s_lshl_b32 s74, s45, 1
	s_mov_b32 s75, 0
	s_mov_b32 s78, 0x168000
	s_mov_b32 s79, 0
	v_mov_b64_e32 v[220:221], s[16:17]
	v_mad_i64_i32 v[220:221], s[56:57], v136, s40, v[220:221]
	v_lshl_add_u64 v[220:221], v[220:221], 0, s[74:75]
	v_lshl_add_u64 v[220:221], v[220:221], 0, v[222:223]
	v_lshl_add_u64 v[220:221], v[220:221], 0, s[26:27]
	global_load_dwordx4 v[244:247], v[220:221], off offset:2048
	global_load_dwordx4 v[248:251], v[220:221], off offset:2064
	s_branch .LBB0_1126

; #define LAS __attribute__((address_space(3)))
; __device__ __forceinline__ unsigned pk2(float lo, float hi) { const f32x2 v = {lo, hi}; return __builtin_bit_cast(unsigned, __builtin_convertvector(v, hbf2)); }
; __device__ __forceinline__ void gdn_chain(LAS unsigned char* lds, const GdnP& P, const float* out_norm, int bh, const int tid) {
;     ...
;     for (int n = 0; n < 64; ++n) {
;         const int row0 = (b * 64 + n) * 64;
;         chain_load(nxt, P, b, h, n < 63 ? n + 1 : n, w, mt, nh, lane, tid);
;         f32x4 oacc[4];
; #pragma unroll
;         for (int q = 0; q < 4; ++q) { const int nt = 4 * nh + q; f32x4 a1 = (f32x4){0.f, 0.f, 0.f, 0.f}; oacc[q] = (f32x4){0.f, 0.f, 0.f, 0.f};
; #pragma unroll
;             for (int s = 0; s < 4; ++s) { const bf16x8 sf = *(const LAS bf16x8*)(lds + GC_ST + (nt * 16 + l15) * 272 + (quad * 8 + 32 * s) * 2);
;                 a1 = __builtin_amdgcn_mfma_f32_16x16x32_bf16(cur.wf[s], sf, a1, 0, 0, 0); oacc[q] = __builtin_amdgcn_mfma_f32_16x16x32_bf16(cur.qf[s], sf, oacc[q], 0, 0, 0); }
;             const unsigned u01 = cur.uf[q >> 1][(q & 1) * 2], u23 = cur.uf[q >> 1][(q & 1) * 2 + 1];
;             u32x2 pv; pv.x = pk2(bflo(u01) - a1[0], bfhi(u01) - a1[1]); pv.y = pk2(bflo(u23) - a1[2], bfhi(u23) - a1[3]);
;             *(LAS u32x2*)(lds + GC_VT + (nt * 16 + l15) * 144 + (mt * 16 + quad * 4) * 2) = pv; }
;     ...
;         for (int nt = 0; nt < 8; ++nt) { sacc[nt] = sacc[nt] * cur.cd;
.LBB0_1126:
	s_waitcnt vmcnt(14)
	v_mov_b64_e32 v[90:91], v[74:75]
	v_mov_b64_e32 v[88:89], v[72:73]
	ds_read_b128 v[72:75], v161
	ds_read_b128 v[92:95], v161 offset:64
	s_waitcnt vmcnt(13)
	v_mov_b64_e32 v[106:107], v[14:15]
	v_mov_b64_e32 v[104:105], v[12:13]
	s_waitcnt vmcnt(10)
	v_mov_b64_e32 v[110:111], v[22:23]
	s_waitcnt lgkmcnt(1)
	v_mfma_f32_16x16x32_bf16 v[96:99], v[88:91], v[72:75], 0
	s_waitcnt vmcnt(8)
	v_mov_b64_e32 v[102:103], v[30:31]
	v_mov_b64_e32 v[108:109], v[20:21]
	ds_read_b128 v[20:23], v161 offset:128
	v_mov_b64_e32 v[100:101], v[28:29]
	s_waitcnt lgkmcnt(1)
	v_mfma_f32_16x16x32_bf16 v[28:31], v[104:107], v[92:95], v[96:99]
	v_mov_b64_e32 v[180:181], v[18:19]
	v_mov_b64_e32 v[184:185], v[6:7]
	v_mov_b64_e32 v[178:179], v[16:17]
	v_mov_b64_e32 v[182:183], v[4:5]
	ds_read_b128 v[4:7], v161 offset:192
	s_waitcnt lgkmcnt(1)
	v_mfma_f32_16x16x32_bf16 v[16:19], v[108:111], v[20:23], v[28:31]
	v_mov_b64_e32 v[188:189], v[2:3]
	v_mov_b64_e32 v[186:187], v[0:1]
	s_waitcnt vmcnt(7)
	v_mov_b64_e32 v[192:193], v[10:11]
	v_mfma_f32_16x16x32_bf16 v[12:15], v[100:103], v[72:75], 0
	v_mov_b64_e32 v[190:191], v[8:9]
	s_waitcnt vmcnt(1)
	v_lshlrev_b32_e32 v8, 16, v80
	v_and_b32_e32 v9, 0xffff0000, v80
	s_waitcnt lgkmcnt(0)
	v_mfma_f32_16x16x32_bf16 v[0:3], v[178:181], v[4:7], v[16:19]
	s_add_i32 s0, s47, 0x41
	s_cmp_lg_u32 s47, -1
	s_cselect_b32 s0, s0, 63
	s_add_i32 s0, s0, s44
	s_lshl_b32 s30, s0, 3
	s_nop 2
	v_pk_add_f32 v[0:1], v[8:9], v[0:1] neg_lo:[0,1] neg_hi:[0,1]
	v_mfma_f32_16x16x32_bf16 v[8:11], v[182:185], v[92:95], v[12:15]
	v_cvt_pk_bf16_f32 v0, v0, v1
	s_or_b32 s30, s30, s43
	s_lshl_b32 s50, s0, 6
	v_lshlrev_b32_e32 v12, 16, v81
	v_and_b32_e32 v13, 0xffff0000, v81
	v_pk_add_f32 v[2:3], v[12:13], v[2:3] neg_lo:[0,1] neg_hi:[0,1]
	v_mfma_f32_16x16x32_bf16 v[8:11], v[186:189], v[20:23], v[8:11]
	v_cvt_pk_bf16_f32 v1, v2, v3
	v_add_u32_e32 v2, v155, v156
	ds_write_b64 v2, v[0:1] offset:34816
	ds_read_b128 v[0:3], v162
	v_mfma_f32_16x16x32_bf16 v[198:201], v[190:193], v[4:7], v[8:11]
	ds_read_b128 v[4:7], v162 offset:64
	ds_read_b128 v[12:15], v162 offset:128
	s_ashr_i32 s31, s30, 31
	s_waitcnt lgkmcnt(2)
	v_mfma_f32_16x16x32_bf16 v[8:11], v[88:91], v[0:3], 0
	v_mov_b64_e32 v[94:95], v[38:39]
	s_lshl_b64 s[48:49], s[30:31], 14
	v_or_b32_e32 v18, s50, v152
	v_mfma_f32_16x16x32_bf16 v[0:3], v[100:103], v[0:3], 0
	v_mov_b64_e32 v[202:203], s[16:17]
	v_mov_b64_e32 v[92:93], v[36:37]
	v_lshl_add_u64 v[16:17], v[132:133], 0, s[48:49]
	s_waitcnt lgkmcnt(1)
	v_mfma_f32_16x16x32_bf16 v[8:11], v[104:107], v[4:7], v[8:11]
	s_lshl_b32 s0, s45, 1
	v_mov_b64_e32 v[196:197], v[70:71]
	v_mov_b64_e32 v[194:195], v[68:69]
	v_mfma_f32_16x16x32_bf16 v[0:3], v[182:185], v[4:7], v[0:3]
	ds_read_b128 v[4:7], v162 offset:192
	v_mov_b64_e32 v[208:209], v[46:47]
	v_mov_b64_e32 v[98:99], v[50:51]
	s_waitcnt lgkmcnt(1)
	v_mfma_f32_16x16x32_bf16 v[8:11], v[108:111], v[12:15], v[8:11]
	v_mov_b64_e32 v[206:207], v[44:45]
	v_mov_b64_e32 v[96:97], v[48:49]
	v_add_u32_e32 v80, s50, v153
	s_waitcnt lgkmcnt(0)
	v_mfma_f32_16x16x32_bf16 v[8:11], v[178:181], v[4:7], v[8:11]
	v_mov_b32_e32 v138, v123
	v_mov_b32_e32 v123, v115
	v_mov_b32_e32 v127, v115
	v_mfma_f32_16x16x32_bf16 v[0:3], v[186:189], v[12:15], v[0:3]
	v_lshlrev_b32_e32 v14, 16, v82
	v_and_b32_e32 v15, 0xffff0000, v82
	s_nop 1
	v_pk_add_f32 v[8:9], v[14:15], v[8:9] neg_lo:[0,1] neg_hi:[0,1]
	v_lshlrev_b32_e32 v14, 16, v83
	v_and_b32_e32 v15, 0xffff0000, v83
	v_pk_add_f32 v[10:11], v[14:15], v[10:11] neg_lo:[0,1] neg_hi:[0,1]
	v_cvt_pk_bf16_f32 v8, v8, v9
	v_cvt_pk_bf16_f32 v9, v10, v11
	v_add_u32_e32 v10, v155, v157
	ds_write_b64 v10, v[8:9] offset:34816
	ds_read_b128 v[8:11], v163
	ds_read_b128 v[36:39], v163 offset:64
	v_mad_i64_i32 v[12:13], s[48:49], v18, s40, v[202:203]
	v_lshl_add_u64 v[12:13], v[12:13], 0, s[0:1]
	s_waitcnt lgkmcnt(1)
	v_mfma_f32_16x16x32_bf16 v[28:31], v[88:91], v[8:11], 0
	s_lshl_b64 s[48:49], s[30:31], 13
	v_lshl_add_u64 v[218:219], v[134:135], 0, s[48:49]
	v_mad_i64_i32 v[80:81], s[48:49], v80, s40, v[202:203]
	v_mfma_f32_16x16x32_bf16 v[210:213], v[190:193], v[4:7], v[0:3]
	s_lshl_b64 s[30:31], s[30:31], 2
	s_add_u32 s30, s2, s30
	s_addc_u32 s31, s3, s31
	v_lshl_add_u64 v[0:1], v[12:13], 0, v[114:115]
	v_add_co_u32_e32 v70, vcc, s41, v0
	v_lshl_add_u64 v[68:69], v[0:1], 0, s[22:23]
	s_nop 0
	v_addc_co_u32_e32 v71, vcc, 0, v1, vcc
	global_load_dwordx4 v[72:75], v[16:17], off
	global_load_dwordx4 v[12:15], v[16:17], off offset:64
	v_mfma_f32_16x16x32_bf16 v[44:47], v[100:103], v[8:11], 0
	global_load_dwordx4 v[4:7], v[68:69], off offset:64
	global_load_dwordx4 v[0:3], v[68:69], off offset:128
	global_load_dwordx4 v[20:23], v[16:17], off offset:128
	s_nop 0
	global_load_dwordx4 v[16:19], v[16:17], off offset:192
	v_pk_mul_f32 v[66:67], v[66:67], v[138:139] op_sel_hi:[1,0]
	v_pk_mul_f32 v[64:65], v[64:65], v[138:139] op_sel_hi:[1,0]
	s_waitcnt lgkmcnt(0)
	v_mfma_f32_16x16x32_bf16 v[48:51], v[104:107], v[36:39], v[28:31]
	s_nop 2
	global_load_dwordx4 v[28:31], v[70:71], off offset:2048
	global_load_dwordx4 v[8:11], v[68:69], off offset:192
	ds_read_b128 v[68:71], v163 offset:128
	v_pk_mul_f32 v[62:63], v[62:63], v[138:139] op_sel_hi:[1,0]
	v_mfma_f32_16x16x32_bf16 v[36:39], v[182:185], v[36:39], v[44:47]
	v_mul_f32_e64 v60, v60, v138
	v_mul_f32_e64 v61, v61, v138
	v_pk_mul_f32 v[58:59], v[58:59], v[138:139] op_sel_hi:[1,0]
	v_pk_mul_f32 v[56:57], v[56:57], v[138:139] op_sel_hi:[1,0]
	ds_read_b128 v[44:47], v163 offset:192
	s_waitcnt lgkmcnt(1)
; #define LAS __attribute__((address_space(3)))
; __device__ __forceinline__ unsigned pk2(float lo, float hi) { const f32x2 v = {lo, hi}; return __builtin_bit_cast(unsigned, __builtin_convertvector(v, hbf2)); }
; __device__ __forceinline__ unsigned f2bf(float f) { return pk2(f, 0.f) & 0xffffu; }
; __device__ __forceinline__ void gdn_chain(LAS unsigned char* lds, const GdnP& P, const float* out_norm, int bh, const int tid) {
;     ...
;         for (int q = 0; q < 4; ++q) { const int nt = 4 * nh + q; f32x4 a1 = (f32x4){0.f, 0.f, 0.f, 0.f}; oacc[q] = (f32x4){0.f, 0.f, 0.f, 0.f};
; #pragma unroll
;             for (int s = 0; s < 4; ++s) { const bf16x8 sf = *(const LAS bf16x8*)(lds + GC_ST + (nt * 16 + l15) * 272 + (quad * 8 + 32 * s) * 2);
;                 a1 = __builtin_amdgcn_mfma_f32_16x16x32_bf16(cur.wf[s], sf, a1, 0, 0, 0); oacc[q] = __builtin_amdgcn_mfma_f32_16x16x32_bf16(cur.qf[s], sf, oacc[q], 0, 0, 0); }
;             const unsigned u01 = cur.uf[q >> 1][(q & 1) * 2], u23 = cur.uf[q >> 1][(q & 1) * 2 + 1];
;             u32x2 pv; pv.x = pk2(bflo(u01) - a1[0], bfhi(u01) - a1[1]); pv.y = pk2(bflo(u23) - a1[2], bfhi(u23) - a1[3]);
;             *(LAS u32x2*)(lds + GC_VT + (nt * 16 + l15) * 144 + (mt * 16 + quad * 4) * 2) = pv; }
;         lds_barrier();
;         float ss[4] = {0.f, 0.f, 0.f, 0.f};
; #pragma unroll
;         for (int q = 0; q < 4; ++q) { const int nt = 4 * nh + q;
; #pragma unroll
;             for (int s = 0; s < 2; ++s) { const bf16x8 vf = *(const LAS bf16x8*)(lds + GC_VT + (nt * 16 + l15) * 144 + (quad * 8 + 32 * s) * 2); oacc[q] = __builtin_amdgcn_mfma_f32_16x16x32_bf16(cur.af[s], vf, oacc[q], 0, 0, 0); }
; #pragma unroll
;             for (int i = 0; i < 4; ++i) { ss[i] += oacc[q][i] * oacc[q][i]; *(LAS bf16_t*)(lds + GC_OB + (mt * 16 + quad * 4 + i) * 272 + (nt * 16 + l15) * 2) = (bf16_t)f2bf(oacc[q][i]); } }
; #pragma unroll
;         for (int nt = 0; nt < 8; ++nt) { sacc[nt] = sacc[nt] * cur.cd;
; #pragma unroll
;             for (int s = 0; s < 2; ++s) { const bf16x8 vf = *(const LAS bf16x8*)(lds + GC_VT + (nt * 16 + l15) * 144 + (quad * 8 + 32 * s) * 2); sacc[nt] = __builtin_amdgcn_mfma_f32_16x16x32_bf16(cur.kf[s], vf, sacc[nt], 0, 0, 0); }
;             u32x2 pv; pv.x = pk2(sacc[nt][0], sacc[nt][1]); pv.y = pk2(sacc[nt][2], sacc[nt][3]);
;             *(LAS u32x2*)(lds + GC_ST + (nt * 16 + l15) * 272 + (w * 16 + quad * 4) * 2) = pv; }
	v_mfma_f32_16x16x32_bf16 v[48:51], v[108:111], v[68:71], v[48:51]
	v_mul_f32_e64 v54, v54, v138
	v_mul_f32_e64 v55, v55, v138
	v_pk_mul_f32 v[52:53], v[52:53], v[138:139] op_sel_hi:[1,0]
	v_pk_mul_f32 v[42:43], v[42:43], v[138:139] op_sel_hi:[1,0]
	s_waitcnt lgkmcnt(0)
	v_mfma_f32_16x16x32_bf16 v[48:51], v[178:181], v[44:47], v[48:51]
	v_mul_f32_e64 v40, v40, v138
	v_mul_f32_e64 v41, v41, v138
	v_pk_mul_f32 v[34:35], v[34:35], v[138:139] op_sel_hi:[1,0]
	v_pk_mul_f32 v[32:33], v[32:33], v[138:139] op_sel_hi:[1,0]
	v_mfma_f32_16x16x32_bf16 v[36:39], v[186:189], v[68:71], v[36:39]
	s_waitcnt vmcnt(8)
	v_lshlrev_b32_e32 v70, 16, v84
	v_and_b32_e32 v71, 0xffff0000, v84
	v_pk_add_f32 v[48:49], v[70:71], v[48:49] neg_lo:[0,1] neg_hi:[0,1]
	v_lshlrev_b32_e32 v70, 16, v85
	v_and_b32_e32 v71, 0xffff0000, v85
	v_pk_add_f32 v[50:51], v[70:71], v[50:51] neg_lo:[0,1] neg_hi:[0,1]
	v_cvt_pk_bf16_f32 v48, v48, v49
	v_cvt_pk_bf16_f32 v49, v50, v51
	v_add_u32_e32 v50, v155, v158
	ds_write_b64 v50, v[48:49] offset:34816
	ds_read_b128 v[48:51], v164
	v_lshl_add_u64 v[68:69], v[80:81], 0, s[0:1]
	ds_read_b128 v[80:83], v164 offset:64
	v_lshl_add_u64 v[68:69], v[68:69], 0, v[122:123]
	s_waitcnt lgkmcnt(1)
	v_mfma_f32_16x16x32_bf16 v[88:91], v[88:91], v[48:51], 0
	v_add_u32_e32 v84, s50, v154
	v_pk_mul_f32 v[26:27], v[26:27], v[138:139] op_sel_hi:[1,0]
	v_pk_mul_f32 v[24:25], v[24:25], v[138:139] op_sel_hi:[1,0]
	v_mfma_f32_16x16x32_bf16 v[214:217], v[190:193], v[44:47], v[36:39]
	v_mul_f32_e64 v78, v78, v138
	v_mul_f32_e64 v79, v79, v138
	v_pk_mul_f32 v[76:77], v[76:77], v[138:139] op_sel_hi:[1,0]
	v_lshl_add_u64 v[36:37], v[68:69], 0, v[114:115]
	v_lshl_add_u64 v[38:39], v[36:37], 0, s[24:25]
	v_add_co_u32_e32 v36, vcc, s38, v36
	global_load_dwordx4 v[68:71], v[218:219], off
	global_load_dwordx4 v[44:47], v[218:219], off offset:64
	v_addc_co_u32_e32 v37, vcc, 0, v37, vcc
	v_mfma_f32_16x16x32_bf16 v[100:103], v[100:103], v[48:51], 0
	global_load_dwordx4 v[48:51], v[36:37], off
	s_nop 0
	global_load_dwordx4 v[36:39], v[38:39], off offset:64
	s_nop 0
	global_load_dword v123, v115, s[30:31]
	s_waitcnt lgkmcnt(0)
	v_mfma_f32_16x16x32_bf16 v[88:91], v[104:107], v[80:83], v[88:91]
	ds_read_b128 v[104:107], v164 offset:128
	v_mad_i64_i32 v[84:85], s[30:31], v84, s40, v[202:203]
	v_mfma_f32_16x16x32_bf16 v[80:83], v[182:185], v[80:83], v[100:103]
	v_lshl_add_u64 v[84:85], v[84:85], 0, s[0:1]
	s_nop 1
	ds_read_b128 v[100:103], v164 offset:192
	s_waitcnt lgkmcnt(1)
	v_mfma_f32_16x16x32_bf16 v[88:91], v[108:111], v[104:107], v[88:91]
	v_mfma_f32_16x16x32_bf16 v[104:107], v[186:189], v[104:107], v[80:83]
	s_nop 2
	v_lshl_add_u64 v[80:81], v[84:85], 0, v[126:127]
	s_waitcnt lgkmcnt(0)
	v_mfma_f32_16x16x32_bf16 v[108:111], v[178:181], v[100:103], v[88:91]
	v_lshl_add_u64 v[84:85], v[80:81], 0, s[26:27]
	v_add_co_u32_e32 v80, vcc, s38, v80
	v_mfma_f32_16x16x32_bf16 v[178:181], v[190:193], v[100:103], v[104:107]
	s_nop 0
	v_addc_co_u32_e32 v81, vcc, 0, v81, vcc
	global_load_dwordx4 v[80:83], v[80:81], off offset:2048
	s_nop 0
	global_load_dwordx4 v[88:91], v[84:85], off offset:16
	v_lshlrev_b32_e32 v84, 16, v86
	v_and_b32_e32 v85, 0xffff0000, v86
	v_lshlrev_b32_e32 v86, 16, v87
	v_and_b32_e32 v87, 0xffff0000, v87
	v_pk_add_f32 v[84:85], v[84:85], v[108:109] neg_lo:[0,1] neg_hi:[0,1]
	v_pk_add_f32 v[86:87], v[86:87], v[110:111] neg_lo:[0,1] neg_hi:[0,1]
	v_cvt_pk_bf16_f32 v84, v84, v85
	v_cvt_pk_bf16_f32 v85, v86, v87
	v_add_u32_e32 v86, v155, v159
	ds_write_b64 v86, v[84:85] offset:34816
	s_waitcnt lgkmcnt(0)
	s_barrier
	ds_read_b128 v[182:185], v148 offset:34816
	ds_read_b128 v[186:189], v148 offset:34880
	ds_read_b128 v[190:193], v148 offset:37120
	ds_read_b128 v[232:235], v148 offset:37184
	s_waitcnt lgkmcnt(2)
	v_mfma_f32_16x16x32_bf16 v[64:67], v[96:99], v[182:185], v[64:67]
	v_mfma_f32_16x16x32_bf16 v[64:67], v[92:95], v[186:189], v[64:67]
	s_cmp_lg_u32 s59, 0
	s_cbranch_scc1 .Lcb_skip0
	v_mfma_f32_16x16x32_bf16 v[84:87], v[194:197], v[182:185], v[198:201]
	v_mfma_f32_16x16x32_bf16 v[84:87], v[206:209], v[186:189], v[84:87]
.Lcb_skip0:
	ds_read_b128 v[182:185], v148 offset:39424
	ds_read_b128 v[186:189], v148 offset:39488
	s_waitcnt lgkmcnt(2)
	v_mfma_f32_16x16x32_bf16 v[60:63], v[96:99], v[190:193], v[60:63]
	v_mfma_f32_16x16x32_bf16 v[60:63], v[92:95], v[232:235], v[60:63]
	s_cmp_lg_u32 s59, 0
	s_cbranch_scc1 .Lcb_skip1
	v_mfma_f32_16x16x32_bf16 v[100:103], v[194:197], v[190:193], v[210:213]
	v_mfma_f32_16x16x32_bf16 v[100:103], v[206:209], v[232:235], v[100:103]
.Lcb_skip1:
	ds_read_b128 v[190:193], v148 offset:41728
	ds_read_b128 v[232:235], v148 offset:41792
	v_cvt_pk_bf16_f32 v218, v64, v65
	v_cvt_pk_bf16_f32 v219, v66, v67
	ds_write_b64 v169, v[218:219]
	s_waitcnt lgkmcnt(3)
	v_mfma_f32_16x16x32_bf16 v[56:59], v[96:99], v[182:185], v[56:59]
	v_mfma_f32_16x16x32_bf16 v[56:59], v[92:95], v[186:189], v[56:59]
	s_cmp_lg_u32 s59, 0
	s_cbranch_scc1 .Lcb_skip2
	v_mfma_f32_16x16x32_bf16 v[104:107], v[194:197], v[182:185], v[214:217]
	v_mfma_f32_16x16x32_bf16 v[104:107], v[206:209], v[186:189], v[104:107]
.Lcb_skip2:
	ds_read_b128 v[182:185], v148 offset:44032
	ds_read_b128 v[186:189], v148 offset:44096
	v_cvt_pk_bf16_f32 v218, v60, v61
	v_cvt_pk_bf16_f32 v219, v62, v63
	ds_write_b64 v169, v[218:219] offset:4352
	s_waitcnt lgkmcnt(4)
	v_mfma_f32_16x16x32_bf16 v[52:55], v[96:99], v[190:193], v[52:55]
	v_mfma_f32_16x16x32_bf16 v[52:55], v[92:95], v[232:235], v[52:55]
	s_cmp_lg_u32 s59, 0
	s_cbranch_scc1 .Lcb_skip3
	v_mfma_f32_16x16x32_bf16 v[108:111], v[194:197], v[190:193], v[178:181]
	v_mfma_f32_16x16x32_bf16 v[108:111], v[206:209], v[232:235], v[108:111]
; #define LAS __attribute__((address_space(3)))
; __device__ __forceinline__ unsigned pk2(float lo, float hi) { const f32x2 v = {lo, hi}; return __builtin_bit_cast(unsigned, __builtin_convertvector(v, hbf2)); }
; __device__ __forceinline__ unsigned f2bf(float f) { return pk2(f, 0.f) & 0xffffu; }
; __device__ __forceinline__ void gdn_chain(LAS unsigned char* lds, const GdnP& P, const float* out_norm, int bh, const int tid) {
;     ...
;         for (int q = 0; q < 4; ++q) { const int nt = 4 * nh + q;
; #pragma unroll
;             for (int s = 0; s < 2; ++s) { const bf16x8 vf = *(const LAS bf16x8*)(lds + GC_VT + (nt * 16 + l15) * 144 + (quad * 8 + 32 * s) * 2); oacc[q] = __builtin_amdgcn_mfma_f32_16x16x32_bf16(cur.af[s], vf, oacc[q], 0, 0, 0); }
; #pragma unroll
;             for (int i = 0; i < 4; ++i) { ss[i] += oacc[q][i] * oacc[q][i]; *(LAS bf16_t*)(lds + GC_OB + (mt * 16 + quad * 4 + i) * 272 + (nt * 16 + l15) * 2) = (bf16_t)f2bf(oacc[q][i]); } }
; #pragma unroll
;         for (int nt = 0; nt < 8; ++nt) { sacc[nt] = sacc[nt] * cur.cd;
; #pragma unroll
;             for (int s = 0; s < 2; ++s) { const bf16x8 vf = *(const LAS bf16x8*)(lds + GC_VT + (nt * 16 + l15) * 144 + (quad * 8 + 32 * s) * 2); sacc[nt] = __builtin_amdgcn_mfma_f32_16x16x32_bf16(cur.kf[s], vf, sacc[nt], 0, 0, 0); }
;             u32x2 pv; pv.x = pk2(sacc[nt][0], sacc[nt][1]); pv.y = pk2(sacc[nt][2], sacc[nt][3]);
;             *(LAS u32x2*)(lds + GC_ST + (nt * 16 + l15) * 272 + (w * 16 + quad * 4) * 2) = pv; }
; #pragma unroll
;         for (int i = 0; i < 4; ++i) { float s = ss[i]; s += __shfl_xor(s, 1); s += __shfl_xor(s, 2); s += __shfl_xor(s, 4); s += __shfl_xor(s, 8); if (l15 == 0) ((LAS float*)(lds + GC_RED))[(mt * 16 + quad * 4 + i) * 2 + nh] = s; }
.Lcb_skip3:
	ds_read_b128 v[190:193], v148 offset:46336
	ds_read_b128 v[232:235], v148 offset:46400
	v_cvt_pk_bf16_f32 v218, v56, v57
	v_cvt_pk_bf16_f32 v219, v58, v59
	ds_write_b64 v169, v[218:219] offset:8704
	s_waitcnt lgkmcnt(4)
	v_mfma_f32_16x16x32_bf16 v[40:43], v[96:99], v[182:185], v[40:43]
	v_mfma_f32_16x16x32_bf16 v[40:43], v[92:95], v[186:189], v[40:43]
	s_cmp_lg_u32 s59, 1
	s_cbranch_scc1 .Lcb_skip4
	v_mfma_f32_16x16x32_bf16 v[84:87], v[194:197], v[182:185], v[198:201]
	v_mfma_f32_16x16x32_bf16 v[84:87], v[206:209], v[186:189], v[84:87]
.Lcb_skip4:
	ds_read_b128 v[182:185], v148 offset:48640
	ds_read_b128 v[186:189], v148 offset:48704
	v_cvt_pk_bf16_f32 v218, v52, v53
	v_cvt_pk_bf16_f32 v219, v54, v55
	ds_write_b64 v169, v[218:219] offset:13056
	s_waitcnt lgkmcnt(4)
	v_mfma_f32_16x16x32_bf16 v[32:35], v[96:99], v[190:193], v[32:35]
	v_mfma_f32_16x16x32_bf16 v[32:35], v[92:95], v[232:235], v[32:35]
	s_cmp_lg_u32 s59, 1
	s_cbranch_scc1 .Lcb_skip5
	v_mfma_f32_16x16x32_bf16 v[100:103], v[194:197], v[190:193], v[210:213]
	v_mfma_f32_16x16x32_bf16 v[100:103], v[206:209], v[232:235], v[100:103]
.Lcb_skip5:
	ds_read_b128 v[190:193], v148 offset:50944
	ds_read_b128 v[232:235], v148 offset:51008
	v_cvt_pk_bf16_f32 v218, v40, v41
	v_cvt_pk_bf16_f32 v219, v42, v43
	ds_write_b64 v169, v[218:219] offset:17408
	s_waitcnt lgkmcnt(4)
	v_mfma_f32_16x16x32_bf16 v[24:27], v[96:99], v[182:185], v[24:27]
	v_mfma_f32_16x16x32_bf16 v[24:27], v[92:95], v[186:189], v[24:27]
	s_cmp_lg_u32 s59, 1
	s_cbranch_scc1 .Lcb_skip6
	v_mfma_f32_16x16x32_bf16 v[104:107], v[194:197], v[182:185], v[214:217]
	v_mfma_f32_16x16x32_bf16 v[104:107], v[206:209], v[186:189], v[104:107]
.Lcb_skip6:
	v_cvt_pk_bf16_f32 v218, v32, v33
	v_cvt_pk_bf16_f32 v219, v34, v35
	ds_write_b64 v169, v[218:219] offset:21760
	s_waitcnt lgkmcnt(2)
	v_mfma_f32_16x16x32_bf16 v[76:79], v[96:99], v[190:193], v[76:79]
	v_mfma_f32_16x16x32_bf16 v[76:79], v[92:95], v[232:235], v[76:79]
	s_cmp_lg_u32 s59, 1
	s_cbranch_scc1 .Lcb_skip7
	v_mfma_f32_16x16x32_bf16 v[108:111], v[194:197], v[190:193], v[178:181]
	v_mfma_f32_16x16x32_bf16 v[108:111], v[206:209], v[232:235], v[108:111]
.Lcb_skip7:
	v_cvt_pk_bf16_f32 v218, v24, v25
	v_cvt_pk_bf16_f32 v219, v26, v27
	ds_write_b64 v169, v[218:219] offset:26112
	s_nop 7
	v_cvt_pk_bf16_f32 v218, v76, v77
	v_cvt_pk_bf16_f32 v219, v78, v79
	ds_write_b64 v169, v[218:219] offset:30464
	v_cvt_pk_bf16_f32 v236, v84, s0
	v_cvt_pk_bf16_f32 v237, v85, s0
	v_cvt_pk_bf16_f32 v240, v86, s0
	v_cvt_pk_bf16_f32 v241, v87, s0
	ds_write_b16 v165, v236 offset:54272
	ds_write_b16 v165, v237 offset:54544
	ds_write_b16 v165, v240 offset:54816
	ds_write_b16 v165, v241 offset:55088
	v_cvt_pk_bf16_f32 v236, v100, s0
	v_cvt_pk_bf16_f32 v237, v101, s0
	v_cvt_pk_bf16_f32 v240, v102, s0
	v_cvt_pk_bf16_f32 v241, v103, s0
	ds_write_b16 v166, v236 offset:54272
	ds_write_b16 v166, v237 offset:54544
	ds_write_b16 v166, v240 offset:54816
	ds_write_b16 v166, v241 offset:55088
	v_cvt_pk_bf16_f32 v236, v104, s0
	v_cvt_pk_bf16_f32 v237, v105, s0
	v_cvt_pk_bf16_f32 v240, v106, s0
	v_cvt_pk_bf16_f32 v241, v107, s0
	ds_write_b16 v167, v236 offset:54272
	ds_write_b16 v167, v237 offset:54544
	ds_write_b16 v167, v240 offset:54816
	ds_write_b16 v167, v241 offset:55088
	v_cvt_pk_bf16_f32 v236, v108, s0
	v_cvt_pk_bf16_f32 v237, v109, s0
	v_cvt_pk_bf16_f32 v240, v110, s0
	v_cvt_pk_bf16_f32 v241, v111, s0
	ds_write_b16 v168, v236 offset:54272
	ds_write_b16 v168, v237 offset:54544
	ds_write_b16 v168, v240 offset:54816
	ds_write_b16 v168, v241 offset:55088
	v_mul_f32_e32 v96, v84, v84
	v_mul_f32_e32 v97, v85, v85
	v_mul_f32_e32 v98, v86, v86
	v_mul_f32_e32 v99, v87, v87
	v_fmac_f32_e32 v96, v100, v100
	v_fmac_f32_e32 v97, v101, v101
	v_fmac_f32_e32 v98, v102, v102
	v_fmac_f32_e32 v99, v103, v103
	v_fmac_f32_e32 v96, v104, v104
	v_fmac_f32_e32 v97, v105, v105
	v_fmac_f32_e32 v98, v106, v106
	v_fmac_f32_e32 v99, v107, v107
	v_fmac_f32_e32 v96, v108, v108
	v_fmac_f32_e32 v97, v109, v109
	v_fmac_f32_e32 v98, v110, v110
	v_fmac_f32_e32 v99, v111, v111
	v_add_f32_dpp v96, v96, v96 row_ror:8 row_mask:0xf bank_mask:0xf
	v_add_f32_dpp v97, v97, v97 row_ror:8 row_mask:0xf bank_mask:0xf
	v_add_f32_dpp v98, v98, v98 row_ror:8 row_mask:0xf bank_mask:0xf
	v_add_f32_dpp v99, v99, v99 row_ror:8 row_mask:0xf bank_mask:0xf
	v_add_f32_dpp v96, v96, v96 row_ror:4 row_mask:0xf bank_mask:0xf
	v_add_f32_dpp v97, v97, v97 row_ror:4 row_mask:0xf bank_mask:0xf
	v_add_f32_dpp v98, v98, v98 row_ror:4 row_mask:0xf bank_mask:0xf
	v_add_f32_dpp v99, v99, v99 row_ror:4 row_mask:0xf bank_mask:0xf
	v_add_f32_dpp v96, v96, v96 row_ror:2 row_mask:0xf bank_mask:0xf
	v_add_f32_dpp v97, v97, v97 row_ror:2 row_mask:0xf bank_mask:0xf
	v_add_f32_dpp v98, v98, v98 row_ror:2 row_mask:0xf bank_mask:0xf
	v_add_f32_dpp v99, v99, v99 row_ror:2 row_mask:0xf bank_mask:0xf
	v_add_f32_dpp v96, v96, v96 row_ror:1 row_mask:0xf bank_mask:0xf
	v_add_f32_dpp v97, v97, v97 row_ror:1 row_mask:0xf bank_mask:0xf
	v_add_f32_dpp v98, v98, v98 row_ror:1 row_mask:0xf bank_mask:0xf
	v_add_f32_dpp v99, v99, v99 row_ror:1 row_mask:0xf bank_mask:0xf
	s_and_saveexec_b64 s[30:31], s[6:7]
	v_add_u32_e32 v127, s46, v160
	ds_write_b32 v127, v96 offset:53248
	ds_write_b32 v170, v97 offset:53248
	ds_write_b32 v171, v98 offset:53248
	ds_write_b32 v172, v99 offset:53248
	s_or_b64 exec, exec, s[30:31]
	s_waitcnt lgkmcnt(0)
	v_mov_b64_e32 v[84:85], s[16:17]
	v_mad_i64_i32 v[84:85], s[30:31], v136, s40, v[84:85]
	s_waitcnt lgkmcnt(0)
	s_barrier
; #define LAS __attribute__((address_space(3)))
; __device__ __forceinline__ unsigned pk2(float lo, float hi) { const f32x2 v = {lo, hi}; return __builtin_bit_cast(unsigned, __builtin_convertvector(v, hbf2)); }
; __device__ __forceinline__ float sigmoidf_(float x) { return __builtin_amdgcn_rcpf(1.f + __builtin_amdgcn_exp2f(-1.4426950408889634f * x)); }
; __device__ __forceinline__ void gdn_chain(LAS unsigned char* lds, const GdnP& P, const float* out_norm, int bh, const int tid) {
;     ...
;         { const int t = tid >> 3, c16 = tid & 7;
;           bf16_t* op = P.proj + (size_t)(row0 + t) * NIN + C_GDN + 2048 + h * 128 + c16 * 16;
;           *(u32x4*)op = *(const LAS u32x4*)(lds + GC_OB + t * 272 + c16 * 32); *(u32x4*)(op + 8) = *(const LAS u32x4*)(lds + GC_OB + t * 272 + c16 * 32 + 16);
;           if (c16 == 0) { const float tot = ((LAS float*)(lds + GC_RED))[t * 2] + ((LAS float*)(lds + GC_RED))[t * 2 + 1]; P.rstdo[(size_t)(row0 + t) * 8 + h] = __builtin_amdgcn_rsqf(tot * (1.f / 128.f) + EPS); } }
; __global__ void __launch_bounds__(NTHREADS, 2) mega(Args a) {
;     ...
;         for (int idx = bx * NTHREADS + tid; idx < TOK * 64; idx += G * NTHREADS) {
;             const int token = idx >> 6, h = (idx >> 3) & 7, c16 = idx & 7;
;             const bf16_t* op = proj + (size_t)token * NIN + C_GDN + 2048 + h * 128 + c16 * 16; bf16_t* zp = proj + (size_t)token * NIN + C_Z + h * 128 + c16 * 16;
;             const u32x4 o0 = *(const u32x4*)op, o1 = *(const u32x4*)(op + 8), z0 = *(const u32x4*)zp, z1 = *(const u32x4*)(zp + 8);
;             const float rstd = rstdo[(size_t)token * 8 + h];
; #pragma unroll
;             for (int hh = 0; hh < 2; ++hh) { const u32x4 ov = hh ? o1 : o0, zv = hh ? z1 : z0;
;                 const f32x4 g0 = *(const f32x4*)(onorm + c16 * 16 + hh * 8), g1 = *(const f32x4*)(onorm + c16 * 16 + hh * 8 + 4);
;                 float r[8];
; #pragma unroll
;                 for (int e = 0; e < 4; ++e) { const float zl = bflo(zv[e]), zh = bfhi(zv[e]); const float gl = (e < 2 ? g0 : g1)[(2 * e) & 3], gh = (e < 2 ? g0 : g1)[(2 * e + 1) & 3];
;                     r[2 * e] = bflo(ov[e]) * rstd * gl * zl * sigmoidf_(zl); r[2 * e + 1] = bfhi(ov[e]) * rstd * gh * zh * sigmoidf_(zh); }
;                 u32x4 o; o.x = pk2(r[0], r[1]); o.y = pk2(r[2], r[3]); o.z = pk2(r[4], r[5]); o.w = pk2(r[6], r[7]);
;                 *(u32x4*)(zp + hh * 8) = o; }
	v_lshl_add_u64 v[84:85], v[84:85], 0, s[0:1]
	v_mov_b32_e32 v131, v115
	v_lshl_add_u64 v[96:97], v[84:85], 0, v[130:131]
	v_lshl_add_u64 v[96:97], v[96:97], 0, s[26:27]
	ds_read_b128 v[84:87], v149 offset:54272
	ds_read_b128 v[92:95], v149 offset:54288
	v_and_b32_e32 v98, 0xfffffff8, v112
	v_add_u32_e32 v98, 0xd000, v98
	ds_read2_b32 v[98:99], v98 offset1:1
	v_lshlrev_b32_e32 v173, 1, v130
	ds_read_b128 v[178:181], v173 offset:53760
	ds_read_b128 v[182:185], v173 offset:53776
	ds_read_b128 v[186:189], v173 offset:53792
	ds_read_b128 v[190:193], v173 offset:53808
	s_waitcnt vmcnt(15) lgkmcnt(0)
	v_add_f32_e32 v98, v98, v99
	v_fmamk_f32 v98, v98, 0x3c000000, v150
	v_rsq_f32_e32 v98, v98
	v_lshlrev_b32_e32 v206, 16, v84
	v_and_b32_e32 v207, 0xffff0000, v84
	v_lshlrev_b32_e32 v208, 16, v85
	v_and_b32_e32 v209, 0xffff0000, v85
	v_lshlrev_b32_e32 v210, 16, v86
	v_and_b32_e32 v211, 0xffff0000, v86
	v_lshlrev_b32_e32 v212, 16, v87
	v_and_b32_e32 v213, 0xffff0000, v87
	v_lshlrev_b32_e32 v214, 16, v92
	v_and_b32_e32 v215, 0xffff0000, v92
	v_lshlrev_b32_e32 v216, 16, v93
	v_and_b32_e32 v217, 0xffff0000, v93
	v_lshlrev_b32_e32 v218, 16, v94
	v_and_b32_e32 v219, 0xffff0000, v94
	v_lshlrev_b32_e32 v240, 16, v95
	v_and_b32_e32 v241, 0xffff0000, v95
	v_lshlrev_b32_e32 v100, 16, v244
	v_and_b32_e32 v101, 0xffff0000, v244
	v_lshlrev_b32_e32 v102, 16, v245
	v_and_b32_e32 v103, 0xffff0000, v245
	v_lshlrev_b32_e32 v104, 16, v246
	v_and_b32_e32 v105, 0xffff0000, v246
	v_lshlrev_b32_e32 v106, 16, v247
	v_and_b32_e32 v107, 0xffff0000, v247
	v_lshlrev_b32_e32 v108, 16, v248
	v_and_b32_e32 v109, 0xffff0000, v248
	v_lshlrev_b32_e32 v110, 16, v249
	v_and_b32_e32 v111, 0xffff0000, v249
	v_lshlrev_b32_e32 v194, 16, v250
	v_and_b32_e32 v195, 0xffff0000, v250
	v_lshlrev_b32_e32 v196, 16, v251
	v_and_b32_e32 v197, 0xffff0000, v251
	v_lshl_add_u64 v[220:221], v[220:221], 0, s[78:79]
	global_load_dwordx4 v[244:247], v[220:221], off offset:2048
	global_load_dwordx4 v[248:251], v[220:221], off offset:2064
	v_mul_f32_e32 v198, 0xbfb8aa3b, v100
	v_mul_f32_e32 v199, 0xbfb8aa3b, v101
	v_mul_f32_e32 v200, 0xbfb8aa3b, v102
	v_mul_f32_e32 v201, 0xbfb8aa3b, v103
	v_mul_f32_e32 v202, 0xbfb8aa3b, v104
	v_mul_f32_e32 v203, 0xbfb8aa3b, v105
	v_mul_f32_e32 v230, 0xbfb8aa3b, v106
	v_mul_f32_e32 v231, 0xbfb8aa3b, v107
	v_mul_f32_e32 v232, 0xbfb8aa3b, v108
	v_mul_f32_e32 v233, 0xbfb8aa3b, v109
	v_mul_f32_e32 v234, 0xbfb8aa3b, v110
	v_mul_f32_e32 v235, 0xbfb8aa3b, v111
	v_mul_f32_e32 v236, 0xbfb8aa3b, v194
	v_mul_f32_e32 v237, 0xbfb8aa3b, v195
	v_mul_f32_e32 v84, 0xbfb8aa3b, v196
	v_mul_f32_e32 v85, 0xbfb8aa3b, v197
	v_exp_f32_e32 v198, v198
	v_exp_f32_e32 v199, v199
	v_exp_f32_e32 v200, v200
	v_exp_f32_e32 v201, v201
	v_exp_f32_e32 v202, v202
	v_exp_f32_e32 v203, v203
	v_exp_f32_e32 v230, v230
	v_exp_f32_e32 v231, v231
	v_exp_f32_e32 v232, v232
	v_exp_f32_e32 v233, v233
	v_exp_f32_e32 v234, v234
	v_exp_f32_e32 v235, v235
	v_exp_f32_e32 v236, v236
	v_exp_f32_e32 v237, v237
	v_exp_f32_e32 v84, v84
	v_exp_f32_e32 v85, v85
	v_pk_mul_f32 v[206:207], v[206:207], v[98:99] op_sel_hi:[1,0]
	v_pk_mul_f32 v[208:209], v[208:209], v[98:99] op_sel_hi:[1,0]
	v_pk_mul_f32 v[210:211], v[210:211], v[98:99] op_sel_hi:[1,0]
	v_pk_mul_f32 v[212:213], v[212:213], v[98:99] op_sel_hi:[1,0]
	v_pk_mul_f32 v[214:215], v[214:215], v[98:99] op_sel_hi:[1,0]
	v_pk_mul_f32 v[216:217], v[216:217], v[98:99] op_sel_hi:[1,0]
	v_pk_mul_f32 v[218:219], v[218:219], v[98:99] op_sel_hi:[1,0]
	v_pk_mul_f32 v[240:241], v[240:241], v[98:99] op_sel_hi:[1,0]
	v_add_f32_e32 v198, 1.0, v198
	v_add_f32_e32 v199, 1.0, v199
	v_add_f32_e32 v200, 1.0, v200
	v_add_f32_e32 v201, 1.0, v201
	v_add_f32_e32 v202, 1.0, v202
	v_add_f32_e32 v203, 1.0, v203
	v_add_f32_e32 v230, 1.0, v230
	v_add_f32_e32 v231, 1.0, v231
	v_add_f32_e32 v232, 1.0, v232
	v_add_f32_e32 v233, 1.0, v233
	v_add_f32_e32 v234, 1.0, v234
	v_add_f32_e32 v235, 1.0, v235
	v_add_f32_e32 v236, 1.0, v236
	v_add_f32_e32 v237, 1.0, v237
	v_add_f32_e32 v84, 1.0, v84
	v_add_f32_e32 v85, 1.0, v85
	v_rcp_f32_e32 v198, v198
	v_rcp_f32_e32 v199, v199
	v_rcp_f32_e32 v200, v200
	v_rcp_f32_e32 v201, v201
	v_rcp_f32_e32 v202, v202
	v_rcp_f32_e32 v203, v203
	v_rcp_f32_e32 v230, v230
	v_rcp_f32_e32 v231, v231
	v_rcp_f32_e32 v232, v232
	v_rcp_f32_e32 v233, v233
	v_rcp_f32_e32 v234, v234
	v_rcp_f32_e32 v235, v235
	v_rcp_f32_e32 v236, v236
	v_rcp_f32_e32 v237, v237
	v_rcp_f32_e32 v84, v84
	v_rcp_f32_e32 v85, v85
	v_pk_mul_f32 v[206:207], v[206:207], v[178:179]
	v_pk_mul_f32 v[208:209], v[208:209], v[180:181]
	v_pk_mul_f32 v[210:211], v[210:211], v[182:183]
	v_pk_mul_f32 v[212:213], v[212:213], v[184:185]
	v_pk_mul_f32 v[214:215], v[214:215], v[186:187]
	v_pk_mul_f32 v[216:217], v[216:217], v[188:189]
	v_pk_mul_f32 v[218:219], v[218:219], v[190:191]
	v_pk_mul_f32 v[240:241], v[240:241], v[192:193]
	v_pk_mul_f32 v[206:207], v[206:207], v[100:101]
	v_pk_mul_f32 v[208:209], v[208:209], v[102:103]
	v_pk_mul_f32 v[210:211], v[210:211], v[104:105]
	v_pk_mul_f32 v[212:213], v[212:213], v[106:107]
	v_pk_mul_f32 v[214:215], v[214:215], v[108:109]
	v_pk_mul_f32 v[216:217], v[216:217], v[110:111]
	v_pk_mul_f32 v[218:219], v[218:219], v[194:195]
	v_pk_mul_f32 v[240:241], v[240:241], v[196:197]
	v_pk_mul_f32 v[206:207], v[206:207], v[198:199]
	v_pk_mul_f32 v[208:209], v[208:209], v[200:201]
	v_pk_mul_f32 v[210:211], v[210:211], v[202:203]
	v_pk_mul_f32 v[212:213], v[212:213], v[230:231]
	v_pk_mul_f32 v[214:215], v[214:215], v[232:233]
	v_pk_mul_f32 v[216:217], v[216:217], v[234:235]
	v_pk_mul_f32 v[218:219], v[218:219], v[236:237]
	v_pk_mul_f32 v[240:241], v[240:241], v[84:85]
	v_cvt_pk_bf16_f32 v100, v206, v207
	v_cvt_pk_bf16_f32 v101, v208, v209
	v_cvt_pk_bf16_f32 v102, v210, v211
	v_cvt_pk_bf16_f32 v103, v212, v213
	v_cvt_pk_bf16_f32 v104, v214, v215
	v_cvt_pk_bf16_f32 v105, v216, v217
	v_cvt_pk_bf16_f32 v106, v218, v219
	v_cvt_pk_bf16_f32 v107, v240, v241
	global_store_dwordx4 v[96:97], v[100:103], off offset:2048
	global_store_dwordx4 v[96:97], v[104:107], off offset:2064
	s_mov_b64 s[30:31], exec
	s_branch .LBB0_1125

; __global__ void __launch_bounds__(NTHREADS, 2) mega(Args a) {
;     ...
;     if (lo <= P_GFIN && P_GFIN < hi) {
;         PHASE_HEAD
;         const float* rstdo = (const float*)(ws + WS_RSTDO); const float* onorm = AIN(I_ONORM);
;         for (int idx = bx * NTHREADS + tid; idx < TOK * 64; idx += G * NTHREADS) {
.LBB0_1327:
	s_cmp_lt_i32 s64, 7
	s_cselect_b64 s[4:5], -1, 0
	s_and_b64 s[0:1], s[4:5], s[0:1]
	s_andn2_b64 vcc, exec, s[0:1]
	s_cbranch_vccnz .LBB0_1332
	s_branch .LBB0_1332
	s_mov_b32 s8, 0
	v_mov_b32_e32 v0, v205
	s_mov_b32 s0, 0x100000
	v_lshl_add_u32 v14, s66, 9, v0
	v_cmp_gt_i32_e32 vcc, s0, v14
	s_and_saveexec_b64 s[0:1], vcc
	s_cbranch_execz .LBB0_1331
	v_readlane_b32 s10, v253, 0
	v_readlane_b32 s11, v253, 1
	s_load_dwordx2 s[2:3], s[10:11], 0xd8
	s_ashr_i32 s9, s8, 31
	v_lshlrev_b32_e32 v0, 4, v0
	v_lshl_add_u32 v15, s66, 13, v0
	s_movk_i32 s16, 0x5a00
	s_waitcnt lgkmcnt(0)
	s_add_u32 s2, s2, s8
	s_addc_u32 s3, s3, s9
	s_add_u32 s12, s2, 0x9300000
	s_addc_u32 s13, s3, 0
	s_add_u32 s6, s2, 0x1f80000
	s_addc_u32 s7, s3, 0
	s_lshl_b64 s[2:3], s[8:9], 3
	s_add_u32 s2, s10, s2
	s_addc_u32 s3, s11, s3
	s_load_dwordx2 s[8:9], s[2:3], 0x58
	s_lshl_b32 s2, s69, 9
	s_lshl_b32 s3, s69, 13
	s_mov_b64 s[10:11], 0
	v_mov_b64_e32 v[8:9], s[12:13]
	v_mov_b32_e32 v11, 0
	s_mov_b64 s[12:13], 0x2800
	s_mov_b64 s[14:15], 0x3000
	s_movk_i32 s17, 0x2000
	s_movk_i32 s18, 0x3000
	s_mov_b32 s19, 0xfffff

; #define GRID_SYNC(k) do { if (lo <= (k) && (k) + 1 < hi) { if (hi > 1000) cg::this_grid().sync(); else xcd_barrier(xbar); } } while (0)
; __global__ void __launch_bounds__(NTHREADS, 2) mega(Args a) {
;     ...
;     GRID_SYNC(P_GFIN);
.LBB0_1332:
	s_cmp_gt_i32 s65, 7
	s_cselect_b64 s[0:1], -1, 0
	s_and_b64 s[0:1], s[4:5], s[0:1]
	s_andn2_b64 vcc, exec, s[0:1]
	s_branch .LBB0_1400
	s_cmpk_lt_u32 s65, 0x3e9
	s_mov_b64 s[0:1], -1
	s_cbranch_scc0 .LBB0_1387
	s_waitcnt vmcnt(0)
	s_waitcnt lgkmcnt(0)
	s_barrier
	s_mov_b64 s[0:1], exec
	v_readlane_b32 s2, v253, 9
	v_readlane_b32 s3, v253, 10
	s_and_b64 s[2:3], s[0:1], s[2:3]
	s_mov_b64 exec, s[2:3]
	s_cbranch_execz .LBB0_1386
	s_add_i32 s2, 0, 0x27500
	v_mov_b32_e32 v0, s2
	s_waitcnt vmcnt(0) expcnt(0) lgkmcnt(0)
	ds_read_b32 v2, v0
	s_add_i32 s2, 0, 0x27504
	v_mov_b32_e32 v0, s2
	ds_read_b32 v0, v0
	s_waitcnt lgkmcnt(1)
	v_cmp_ne_u32_e32 vcc, 0, v2
	s_cbranch_vccnz .LBB0_1350
	v_readlane_b32 s4, v253, 2
	v_readlane_b32 s5, v253, 3
	v_readlane_b32 s10, v253, 6
	s_load_dwordx2 s[2:3], s[4:5], 0x4
	v_readlane_b32 s11, v253, 7
	s_add_u32 s4, s10, 0x1000
	s_addc_u32 s5, s11, 0
	s_add_u32 s6, s10, 0x1100
	s_addc_u32 s7, s11, 0
	s_add_u32 s8, s10, 0x1200
	s_addc_u32 s9, s11, 0
	s_waitcnt lgkmcnt(0)
	s_mul_i32 s2, s2, s69
	s_add_u32 s10, s10, 0x1300
	s_mul_i32 s2, s2, s3
	s_addc_u32 s11, s11, 0
	s_mov_b32 s3, 1
	v_mov_b32_e32 v16, 0
	s_branch .LBB0_1338
